# wait-at-first-consumer: rst table load overlapped with GEMM prologue DMA in P4/P9, q-frag wait moved below BIAS setup, memattn unit header vmcnt dropped
# speedup vs baseline: 1.0008x; 1.0008x over previous
.Lsp_par_done:
	v_readfirstlane_b32 s21, v5
	s_ashr_i32 s20, s21, 6
	s_add_i32 s80, s25, -1
	v_bfe_u32 v0, v5, 4, 2
	s_and_b32 s22, s20, 3
	s_lshl_b32 s26, s20, 3
	s_ashr_i32 s81, s80, 31
	v_or_b32_e32 v4, s26, v0
	v_lshlrev_b32_e32 v6, 5, v0
	v_bitop3_b32 v0, s26, v5, v0 bitop3:0x36
	s_lshl_b32 s30, s22, 5
	s_max_i32 s31, s25, 2
	s_lshl_b64 s[26:27], s[80:81], 16
	v_and_b32_e32 v3, 15, v5
	v_lshlrev_b32_e32 v8, 9, v4
	v_lshlrev_b32_e32 v0, 3, v0
	s_add_u32 s28, s48, s26
	v_lshlrev_b32_e32 v7, 3, v3
	v_and_or_b32 v0, v0, s11, v8
	s_addc_u32 s29, s49, s27
	v_lshlrev_b32_e32 v188, 1, v0
	v_bitop3_b32 v0, v8, v6, v7 bitop3:0xf6
	s_add_u32 s34, s60, s26
	v_lshlrev_b32_e32 v190, 1, v0
	v_or_b32_e32 v0, 4, v4
	v_bitop3_b32 v4, v4, v5, 4 bitop3:0x36
	s_addc_u32 s35, s61, s27
	s_lshl_b32 s26, s20, 11
	v_lshlrev_b32_e32 v0, 9, v0
	v_lshlrev_b32_e32 v4, 3, v4
	s_add_i32 s26, s26, 0
	v_mov_b32_e32 v189, v1
	v_and_or_b32 v4, v4, s11, v0
	s_add_i32 s27, s26, 0x4000
	v_lshl_add_u64 v[8:9], s[28:29], 0, v[188:189]
	s_mov_b32 m0, s26
	s_nop 0
	global_load_lds_dwordx4 v[8:9], off
	v_mov_b32_e32 v191, v1
	v_lshlrev_b32_e32 v192, 1, v4
	v_bitop3_b32 v0, v0, v6, v7 bitop3:0xf6
	v_lshl_add_u64 v[8:9], s[34:35], 0, v[190:191]
	s_mov_b32 m0, s27
	s_nop 0
	global_load_lds_dwordx4 v[8:9], off
	v_mov_b32_e32 v193, v1
	s_add_i32 s27, s26, 0x400
	s_add_i32 s72, s31, -2
	v_lshlrev_b32_e32 v194, 1, v0
	v_lshl_add_u64 v[8:9], s[28:29], 0, v[192:193]
	s_mov_b32 m0, s27
	s_nop 0
	global_load_lds_dwordx4 v[8:9], off
	v_mov_b32_e32 v195, v1
	s_add_i32 s27, s26, 0x4400
	s_ashr_i32 s46, s21, 8
	s_lshl_b64 s[28:29], s[72:73], 16
	v_lshl_add_u64 v[8:9], s[34:35], 0, v[194:195]
	s_add_u32 s34, s48, s28
	s_addc_u32 s35, s49, s29
	s_add_u32 s28, s60, s28
	s_mov_b32 m0, s27
	s_nop 0
	global_load_lds_dwordx4 v[8:9], off
	s_addc_u32 s29, s61, s29
	v_lshl_add_u64 v[8:9], s[34:35], 0, v[188:189]
	v_and_b32_e32 v2, 31, v5
	s_add_i32 s27, s26, 0x8000
	s_mov_b32 m0, s27
	s_nop 0
	global_load_lds_dwordx4 v[8:9], off
	v_lshl_add_u64 v[8:9], s[28:29], 0, v[190:191]
	s_add_i32 s31, s26, 0xc000
	s_mov_b32 m0, s31
	s_nop 0
	global_load_lds_dwordx4 v[8:9], off
	v_lshl_add_u64 v[8:9], s[34:35], 0, v[192:193]
	v_or_b32_e32 v226, s30, v2
	s_add_i32 s27, s26, 0x8400
	s_mov_b32 m0, s27
	s_nop 0
	global_load_lds_dwordx4 v[8:9], off
	v_lshl_add_u64 v[8:9], s[28:29], 0, v[194:195]
	v_lshlrev_b32_e32 v0, 11, v226
	s_lshl_b32 s28, s46, 6
	v_bfe_u32 v4, v5, 5, 1
	s_add_i32 s27, s26, 0xc400
	s_mov_b32 m0, s27
	s_nop 0
	global_load_lds_dwordx4 v[8:9], off
	v_lshl_add_u64 v[8:9], s[38:39], 0, v[0:1]
	s_ashr_i32 s29, s28, 31
	v_lshl_add_u64 v[8:9], s[28:29], 1, v[8:9]
	v_lshlrev_b32_e32 v0, 4, v4
	v_lshl_add_u64 v[8:9], v[8:9], 0, v[0:1]
	global_load_dwordx4 v[144:147], v[8:9], off
	global_load_dwordx4 v[148:151], v[8:9], off offset:32
	global_load_dwordx4 v[152:155], v[8:9], off offset:64
	global_load_dwordx4 v[156:159], v[8:9], off offset:96
	v_readlane_b32 s12, v253, 34
	v_readlane_b32 s13, v253, 35
	v_and_b32_e32 v203, 63, v5
	s_or_b64 s[82:83], s[0:1], s[12:13]
	v_mov_b32_e32 v231, 0x7f61b1e6
	s_and_b64 vcc, exec, s[82:83]
	v_cmp_eq_u32_e64 s[0:1], 0, v203
	s_cbranch_vccnz .LBB0_455
	s_waitcnt vmcnt(0)
	s_lshl_b32 s72, s36, 1
	s_lshl_b64 s[28:29], s[72:73], 2
	v_readlane_b32 s12, v253, 25
	v_readlane_b32 s13, v253, 26
	s_add_u32 s27, s12, s28
	s_addc_u32 s31, s13, s29
	v_and_b32_e32 v7, 0xffff0000, v144
	s_ashr_i32 s47, s46, 31
	v_lshlrev_b32_e32 v0, 16, v144
	v_mul_f32_e32 v7, v7, v7
	s_lshl_b64 s[28:29], s[46:47], 2
	v_fmac_f32_e32 v7, v0, v0
	v_lshlrev_b32_e32 v0, 16, v145
	s_add_u32 s28, s27, s28
	v_fmac_f32_e32 v7, v0, v0
	v_and_b32_e32 v0, 0xffff0000, v145
	s_addc_u32 s29, s31, s29
	v_fmac_f32_e32 v7, v0, v0
	global_load_dword v0, v1, s[28:29]
	v_lshlrev_b32_e32 v8, 16, v146
	v_fmac_f32_e32 v7, v8, v8
	v_and_b32_e32 v8, 0xffff0000, v146
	v_fmac_f32_e32 v7, v8, v8
	v_lshlrev_b32_e32 v8, 16, v147
	v_fmac_f32_e32 v7, v8, v8
	v_and_b32_e32 v8, 0xffff0000, v147
	v_fmac_f32_e32 v7, v8, v8
	v_lshlrev_b32_e32 v8, 16, v148
	v_fmac_f32_e32 v7, v8, v8
	v_and_b32_e32 v8, 0xffff0000, v148
	v_fmac_f32_e32 v7, v8, v8
	v_lshlrev_b32_e32 v8, 16, v149
	v_fmac_f32_e32 v7, v8, v8
	v_and_b32_e32 v8, 0xffff0000, v149
	v_fmac_f32_e32 v7, v8, v8
	v_lshlrev_b32_e32 v8, 16, v150
	v_fmac_f32_e32 v7, v8, v8
	v_and_b32_e32 v8, 0xffff0000, v150
	v_fmac_f32_e32 v7, v8, v8
	v_lshlrev_b32_e32 v8, 16, v151
	v_fmac_f32_e32 v7, v8, v8
	v_and_b32_e32 v8, 0xffff0000, v151
	v_fmac_f32_e32 v7, v8, v8
	v_lshlrev_b32_e32 v8, 16, v152
	v_fmac_f32_e32 v7, v8, v8
	v_and_b32_e32 v8, 0xffff0000, v152
	v_fmac_f32_e32 v7, v8, v8
	v_lshlrev_b32_e32 v8, 16, v153
	v_fmac_f32_e32 v7, v8, v8
	v_and_b32_e32 v8, 0xffff0000, v153
	v_fmac_f32_e32 v7, v8, v8
	v_lshlrev_b32_e32 v8, 16, v154
	v_fmac_f32_e32 v7, v8, v8
	v_and_b32_e32 v8, 0xffff0000, v154
	v_fmac_f32_e32 v7, v8, v8
	v_lshlrev_b32_e32 v8, 16, v155
	v_fmac_f32_e32 v7, v8, v8
	v_and_b32_e32 v8, 0xffff0000, v155
	v_fmac_f32_e32 v7, v8, v8
	v_and_b32_e32 v9, 0xffff0000, v156
	v_lshlrev_b32_e32 v8, 16, v156
	v_pk_mul_f32 v[8:9], v[8:9], v[8:9]
	s_mov_b32 s12, 0xf800000
	v_add_f32_e32 v7, v8, v7
	v_add_f32_e32 v7, v9, v7
	v_and_b32_e32 v9, 0xffff0000, v157
	v_lshlrev_b32_e32 v8, 16, v157
	v_pk_mul_f32 v[8:9], v[8:9], v[8:9]
	s_nop 0
	v_add_f32_e32 v7, v8, v7
	v_add_f32_e32 v7, v9, v7
	v_and_b32_e32 v9, 0xffff0000, v158
	v_lshlrev_b32_e32 v8, 16, v158
	v_pk_mul_f32 v[8:9], v[8:9], v[8:9]
	s_nop 0
	v_add_f32_e32 v7, v8, v7
	v_add_f32_e32 v7, v9, v7
	v_and_b32_e32 v9, 0xffff0000, v159
	v_lshlrev_b32_e32 v8, 16, v159
	v_pk_mul_f32 v[8:9], v[8:9], v[8:9]
	s_nop 0
	v_add_f32_e32 v7, v8, v7
	v_add_f32_e32 v7, v9, v7
	ds_bpermute_b32 v8, v225, v7
	s_waitcnt lgkmcnt(0)
	v_add_f32_e32 v7, v7, v8
	v_mul_f32_e32 v8, 0x4f800000, v7
	v_cmp_gt_f32_e32 vcc, s12, v7
	s_nop 1
	v_cndmask_b32_e32 v7, v7, v8, vcc
	v_sqrt_f32_e32 v8, v7
	s_nop 0
	v_add_u32_e32 v9, -1, v8
	v_fma_f32 v10, -v9, v8, v7
	v_cmp_ge_f32_e64 s[38:39], 0, v10
	v_add_u32_e32 v10, 1, v8
	v_fma_f32 v11, -v10, v8, v7
	v_cmp_lt_f32_e64 s[42:43], 0, v11
	s_and_saveexec_b64 s[84:85], s[0:1]
	s_cbranch_execz .LBB0_454
	s_lshl_b32 s0, s20, 2
	s_add_i32 s0, s0, 0
	s_add_i32 s0, s0, 0x20040
	v_mov_b32_e32 v11, s0
	ds_write_b32 v11, v1
	ds_write_b32 v11, v1 offset:32

.LBB0_455:
	v_lshrrev_b32_e32 v0, 2, v3
	v_lshlrev_b32_e32 v7, 10, v4
	v_lshlrev_b32_e32 v8, 8, v0
	v_and_b32_e32 v6, 32, v6
	v_lshlrev_b32_e32 v5, 3, v5
	v_or3_b32 v6, v7, v8, v6
	v_and_b32_e32 v5, 24, v5
	v_lshlrev_b32_e32 v0, 6, v0
	v_or3_b32 v0, v6, v5, v0
	s_movk_i32 s0, 0x80
	v_bitop3_b32 v229, v0, s0, v217 bitop3:0x36
	s_movk_i32 s0, 0xc0
	s_cmp_gt_i32 s20, 3
	v_lshlrev_b32_e32 v202, 2, v4
	v_or_b32_e32 v227, 0x4000, v0
	v_bitop3_b32 v228, v0, 64, v217 bitop3:0x36
	v_bitop3_b32 v230, v0, s0, v217 bitop3:0x36
	s_mov_b64 s[84:85], -1
	s_cmp_lt_i32 s25, 1
	s_mov_b32 s27, 0
	s_cbranch_scc1 .LBB0_498
	s_not_b32 s1, s23
	s_lshl_b32 s1, s1, 1
	v_ldexp_f32 v0, 1.0, s1
	v_or_b32_e32 v198, s24, v226
	v_mul_f32_e32 v196, 0x3fb8aa3b, v0
	v_sub_u32_e32 v0, v202, v198
	v_add_u32_e32 v5, 1, v0
	v_cvt_f32_i32_e32 v6, v0
	v_cvt_f32_i32_e32 v7, v5
	v_add_u32_e32 v5, 2, v0
	v_add_u32_e32 v8, 3, v0
	v_cvt_f32_i32_e32 v9, v8
	v_cvt_f32_i32_e32 v8, v5
	v_add_u32_e32 v5, 8, v0
	v_add_u32_e32 v10, 9, v0
	v_cvt_f32_i32_e32 v11, v10
	v_cvt_f32_i32_e32 v10, v5
	v_mov_b32_e32 v197, v196
	v_add_u32_e32 v5, 10, v0
	v_add_u32_e32 v12, 11, v0
	v_cvt_f32_i32_e32 v13, v12
	v_cvt_f32_i32_e32 v12, v5
	v_pk_mul_f32 v[80:81], v[196:197], v[6:7] op_sel_hi:[0,1]
	v_add_u32_e32 v5, 16, v0
	v_add_u32_e32 v6, 17, v0
	v_pk_mul_f32 v[82:83], v[196:197], v[8:9] op_sel_hi:[0,1]
	v_cvt_f32_i32_e32 v7, v6
	v_cvt_f32_i32_e32 v6, v5
	v_add_u32_e32 v5, 18, v0
	v_add_u32_e32 v8, 19, v0
	v_pk_mul_f32 v[84:85], v[196:197], v[10:11] op_sel_hi:[0,1]
	v_cvt_f32_i32_e32 v9, v8
	v_cvt_f32_i32_e32 v8, v5
	v_add_u32_e32 v5, 24, v0
	v_add_u32_e32 v10, 25, v0
	v_cvt_f32_i32_e32 v11, v10
	v_cvt_f32_i32_e32 v10, v5
	v_pk_mul_f32 v[86:87], v[196:197], v[12:13] op_sel_hi:[0,1]
	v_add_u32_e32 v5, 26, v0
	v_add_u32_e32 v12, 27, v0
	v_cvt_f32_i32_e32 v13, v12
	v_cvt_f32_i32_e32 v12, v5
	v_pk_mul_f32 v[88:89], v[196:197], v[6:7] op_sel_hi:[0,1]
	v_add_u32_e32 v5, 32, v0
	v_add_u32_e32 v6, 33, v0
	v_pk_mul_f32 v[90:91], v[196:197], v[8:9] op_sel_hi:[0,1]
	v_cvt_f32_i32_e32 v7, v6
	v_cvt_f32_i32_e32 v6, v5
	v_add_u32_e32 v5, 34, v0
	v_add_u32_e32 v8, 35, v0
	v_pk_mul_f32 v[92:93], v[196:197], v[10:11] op_sel_hi:[0,1]
	v_cvt_f32_i32_e32 v9, v8
	v_cvt_f32_i32_e32 v8, v5
	v_add_u32_e32 v5, 40, v0
	v_add_u32_e32 v10, 41, v0
	v_cvt_f32_i32_e32 v11, v10
	v_cvt_f32_i32_e32 v10, v5
	v_pk_mul_f32 v[94:95], v[196:197], v[12:13] op_sel_hi:[0,1]
	v_add_u32_e32 v5, 42, v0
	v_add_u32_e32 v12, 43, v0
	v_cvt_f32_i32_e32 v13, v12
	v_cvt_f32_i32_e32 v12, v5
	v_pk_mul_f32 v[96:97], v[196:197], v[6:7] op_sel_hi:[0,1]
	v_add_u32_e32 v5, 48, v0
	v_add_u32_e32 v6, 49, v0
	s_lshl_b32 s0, s20, 2
	v_pk_mul_f32 v[98:99], v[196:197], v[8:9] op_sel_hi:[0,1]
	v_cvt_f32_i32_e32 v7, v6
	v_cvt_f32_i32_e32 v6, v5
	v_add_u32_e32 v5, 50, v0
	v_add_u32_e32 v8, 51, v0
	s_add_i32 s28, s0, 0
	s_lshl_b32 s0, s96, 1
	s_lshr_b32 s1, s22, 1
	v_pk_mul_f32 v[100:101], v[196:197], v[10:11] op_sel_hi:[0,1]
	v_cvt_f32_i32_e32 v9, v8
	v_cvt_f32_i32_e32 v8, v5
	v_add_u32_e32 v5, 56, v0
	v_add_u32_e32 v10, 57, v0
	s_or_b32 s37, s1, s0
	s_cmp_eq_u32 s100, 1
	s_cselect_b32 s98, s101, 0
	s_sub_i32 s37, s37, s98
	s_lshr_b32 s98, s36, 2
	s_lshl_b32 s98, s98, 6
	s_and_b32 s99, s36, 3
	s_lshl_b32 s99, s99, 5
	s_add_i32 s98, s98, s99
	s_add_i32 s98, s98, s96
	s_add_i32 s101, s98, 0xffffffa0
	v_cvt_f32_i32_e32 v11, v10
	v_cvt_f32_i32_e32 v10, v5
	v_add_u32_e32 v5, 58, v0
	v_add_u32_e32 v0, 59, v0
	s_lshl_b32 s0, s46, 3
	v_pk_mul_f32 v[102:103], v[196:197], v[12:13] op_sel_hi:[0,1]
	v_cvt_f32_i32_e32 v13, v0
	v_cvt_f32_i32_e32 v12, v5
	v_lshlrev_b32_e32 v0, 8, v2
	v_or_b32_e32 v5, s0, v4
	v_bitop3_b32 v4, s0, v3, v4 bitop3:0x36
	v_lshl_add_u32 v233, v4, 4, v0
	v_bitop3_b32 v4, v5, v3, 2 bitop3:0x36
	v_lshl_add_u32 v234, v4, 4, v0
	v_bitop3_b32 v4, v5, v3, 4 bitop3:0x36
	v_bitop3_b32 v3, v5, v3, 6 bitop3:0x36
	s_addk_i32 s30, 0x1fc1
	v_lshl_add_u32 v235, v4, 4, v0
	v_lshl_add_u32 v236, v3, 4, v0
	s_lshl_b32 s31, s25, 6
	v_add_u32_e32 v0, s30, v2
	v_subrev_u32_e32 v0, s31, v0
	s_lshl_b32 s19, s19, 7
	v_mov_b32_e32 v14, v1
	v_mov_b32_e32 v15, v1
	v_mov_b32_e32 v172, v1
	v_mov_b32_e32 v173, v1
	s_add_i32 s29, s24, 0x80
	v_pk_mul_f32 v[104:105], v[196:197], v[6:7] op_sel_hi:[0,1]
	v_pk_mul_f32 v[106:107], v[196:197], v[8:9] op_sel_hi:[0,1]
	v_pk_mul_f32 v[108:109], v[196:197], v[10:11] op_sel_hi:[0,1]
	v_pk_mul_f32 v[110:111], v[196:197], v[12:13] op_sel_hi:[0,1]
	s_lshl_b32 s34, s25, 3
	v_subrev_u32_e32 v237, s19, v0
	s_lshl_b32 s19, s25, 5
	v_mov_b32_e32 v0, v1
	v_mov_b32_e32 v2, v1
	v_mov_b32_e32 v3, v1
	v_mov_b32_e32 v4, v1
	v_mov_b32_e32 v5, v1
	v_mov_b32_e32 v6, v1
	v_mov_b32_e32 v7, v1
	v_mov_b32_e32 v8, v1
	v_mov_b32_e32 v9, v1
	v_mov_b32_e32 v10, v1
	v_mov_b32_e32 v11, v1
	v_mov_b32_e32 v12, v1
	v_mov_b32_e32 v13, v1
	v_mov_b32_e32 v174, v1
	v_mov_b32_e32 v175, v1
	v_mov_b64_e32 v[168:169], v[172:173]
	v_mov_b64_e32 v[164:165], v[172:173]
	v_mov_b64_e32 v[160:161], v[172:173]
	v_mov_b64_e32 v[78:79], v[14:15]
	v_mov_b64_e32 v[62:63], v[14:15]
	v_mov_b64_e32 v[46:47], v[14:15]
	v_mov_b64_e32 v[30:31], v[14:15]
	s_xor_b64 s[88:89], s[82:83], -1
	s_add_i32 s28, s28, 0x20040
	v_cmp_eq_u32_e64 s[0:1], 0, v203
	s_mov_b32 s47, s29
	v_mov_b32_e32 v199, v198
	s_sub_i32 s67, s31, 64
	s_add_i32 s72, s34, -16
	s_sub_i32 s81, s19, 32
	s_mov_b64 s[96:97], 0
	v_mov_b32_e32 v201, 0xf149f2ca
	v_mov_b32_e32 v232, 0
	v_mov_b64_e32 v[170:171], v[174:175]
	v_mov_b64_e32 v[166:167], v[174:175]
	v_mov_b64_e32 v[162:163], v[174:175]
	v_mov_b64_e32 v[76:77], v[12:13]
	v_mov_b64_e32 v[74:75], v[10:11]
	v_mov_b64_e32 v[72:73], v[8:9]
	v_mov_b64_e32 v[70:71], v[6:7]
	v_mov_b64_e32 v[68:69], v[4:5]
	v_mov_b64_e32 v[66:67], v[2:3]
	v_mov_b64_e32 v[64:65], v[0:1]
	v_mov_b64_e32 v[60:61], v[12:13]
	v_mov_b64_e32 v[58:59], v[10:11]
	v_mov_b64_e32 v[56:57], v[8:9]
	v_mov_b64_e32 v[54:55], v[6:7]
	v_mov_b64_e32 v[52:53], v[4:5]
	v_mov_b64_e32 v[50:51], v[2:3]
	v_mov_b64_e32 v[48:49], v[0:1]
	v_mov_b64_e32 v[44:45], v[12:13]
	v_mov_b64_e32 v[42:43], v[10:11]
	v_mov_b64_e32 v[40:41], v[8:9]
	v_mov_b64_e32 v[38:39], v[6:7]
	v_mov_b64_e32 v[36:37], v[4:5]
	v_mov_b64_e32 v[34:35], v[2:3]
	v_mov_b64_e32 v[32:33], v[0:1]
	v_mov_b64_e32 v[28:29], v[12:13]
	v_mov_b64_e32 v[26:27], v[10:11]
	v_mov_b64_e32 v[24:25], v[8:9]
	v_mov_b64_e32 v[22:23], v[6:7]
	v_mov_b64_e32 v[20:21], v[4:5]
	v_mov_b64_e32 v[18:19], v[2:3]
	v_mov_b64_e32 v[16:17], v[0:1]
	s_mov_b32 s50, 0
	s_waitcnt vmcnt(0)
	s_branch .LBB0_458

.LBB0_513:
	v_mov_b32_e32 v0, v204
	s_barrier
	s_nop 0
	v_cmp_eq_u32_e32 vcc, 0, v0
	s_and_saveexec_b64 s[36:37], vcc
	s_cbranch_execz .LBB0_517
	s_mov_b64 s[42:43], exec
	v_mbcnt_lo_u32_b32 v0, s42, 0
	v_mbcnt_hi_u32_b32 v0, s43, v0
	v_cmp_eq_u32_e32 vcc, 0, v0
	s_and_saveexec_b64 s[38:39], vcc
	s_cbranch_execz .LBB0_516
	s_bcnt1_i32_b64 s19, s[42:43]
	v_mov_b32_e32 v2, s19
	global_atomic_add v2, v1, v2, s[0:1] sc0

.LBB0_830:
	s_andn2_b64 vcc, exec, s[0:1]
	s_cbranch_vccnz .LBB0_953
	s_and_b64 s[0:1], s[40:41], exec
	v_readlane_b32 s0, v253, 11
	v_readlane_b32 s1, v253, 13
	s_cselect_b32 s37, s0, s1
	v_readlane_b32 s0, v253, 10
	v_readlane_b32 s1, v253, 12
	s_cselect_b32 s36, s0, s1
	v_readlane_b32 s0, v253, 6
	v_readlane_b32 s1, v253, 7
	s_and_b64 vcc, exec, s[0:1]
	v_readlane_b32 s0, v254, 56
	v_readlane_b32 s1, v254, 57
	s_mov_b32 s19, 0
	s_nop 0
	v_cndmask_b32_e64 v0, 0, 1, s[0:1]
	v_cmp_ne_u32_e64 s[0:1], 1, v0
	s_cbranch_vccnz .LBB0_837
	s_and_b64 vcc, exec, s[0:1]
	s_cbranch_vccnz .LBB0_836
	v_mov_b32_e32 v0, v204
	s_movk_i32 s12, 0x100
	s_nop 0
	v_cmp_gt_i32_e32 vcc, s12, v0
	s_and_saveexec_b64 s[38:39], vcc
	s_cbranch_execz .LBB0_835
	v_readlane_b32 s12, v255, 4
	s_nop 1
	v_add_u32_e32 v2, s12, v0
	s_waitcnt lgkmcnt(0)
	v_ashrrev_i32_e32 v3, 31, v2
	v_lshl_add_u64 v[2:3], v[2:3], 3, s[36:37]
	global_load_dwordx2 v[250:251], v[2:3], off
	v_lshl_add_u32 v0, v0, 2, 0
	v_add_u32_e32 v249, 0x20100, v0

.LBB0_836:
.LBB0_837:
	s_and_b64 s[20:21], s[40:41], exec
	s_mov_b32 s20, 0xf00000
	s_cselect_b32 s20, s20, 0x1700000
	s_add_u32 s20, s54, s20
	v_mov_b32_e32 v8, v204
	s_addc_u32 s21, s55, 0
	s_and_b64 vcc, exec, s[0:1]
	v_readfirstlane_b32 s0, v8
	s_cbranch_vccnz .LBB0_889
	v_lshlrev_b32_e32 v0, 4, v8
	v_add_u32_e32 v2, 0x2000, v0
	s_waitcnt lgkmcnt(0)
	v_ashrrev_i32_e32 v3, 31, v2
	v_lshrrev_b32_e32 v3, 22, v3
	v_add_u32_e32 v3, v2, v3
	v_ashrrev_i32_e32 v6, 10, v3
	v_mul_i32_i24_e32 v3, 0x400, v6
	v_sub_u32_e32 v2, v2, v3
	v_lshrrev_b32_e32 v3, 4, v2
	v_bitop3_b32 v2, v3, v2, 32 bitop3:0x6c
	v_ashrrev_i32_e32 v3, 31, v2
	v_lshrrev_b32_e32 v3, 26, v3
	v_add_u32_e32 v3, v2, v3
	v_lshlrev_b32_e32 v4, 3, v6
	v_ashrrev_i32_e32 v7, 6, v3
	v_and_b32_e32 v4, -16, v4
	v_add_u32_e32 v4, v7, v4
	v_and_b32_e32 v5, 3, v7
	s_mov_b32 s12, 0x1fffe0
	v_lshrrev_b32_e32 v9, 2, v4
	v_lshlrev_b32_e32 v10, 1, v4
	v_and_b32_e32 v3, 0xc0, v3
	v_and_or_b32 v5, v4, s12, v5
	v_and_b32_e32 v9, 4, v9
	v_and_b32_e32 v10, 24, v10
	v_sub_u32_e32 v2, v2, v3
	v_or3_b32 v5, v5, v9, v10
	v_lshlrev_b32_e32 v9, 5, v6
	v_ashrrev_i16_sdwa v2, v224, sext(v2) dst_sel:DWORD dst_unused:UNUSED_PAD src0_sel:DWORD src1_sel:BYTE_0
	v_and_b32_e32 v10, 32, v9
	v_bfe_i32 v9, v2, 0, 16
	v_add_lshl_u32 v2, v10, v9, 1
	v_lshl_add_u32 v130, v5, 11, v2
	v_lshl_add_u32 v132, v4, 11, v2
	v_bfe_i32 v2, v8, 27, 1
	v_lshrrev_b32_e32 v2, 22, v2
	v_add_u32_e32 v2, v0, v2
	v_and_b32_e32 v2, 0xfffffc00, v2
	v_sub_u32_e32 v0, v0, v2
	v_lshrrev_b32_e32 v2, 4, v0
	v_bitop3_b32 v2, v2, v0, 32 bitop3:0x6c
	v_ashrrev_i32_e32 v0, 31, v0
	v_lshrrev_b32_e32 v0, 26, v0
	v_add_u32_e32 v0, v2, v0
	v_ashrrev_i32_e32 v10, 6, v0
	v_ashrrev_i32_e32 v0, 31, v8
	v_lshrrev_b32_e32 v0, 26, v0
	v_add_u32_e32 v0, v8, v0
	v_ashrrev_i32_e32 v11, 6, v0
	v_lshlrev_b32_e32 v0, 3, v11
	v_and_b32_e32 v0, -16, v0
	v_add_u32_e32 v3, v10, v0
	v_and_b32_e32 v0, 3, v10
	v_lshrrev_b32_e32 v4, 2, v3
	v_lshlrev_b32_e32 v5, 1, v3
	v_and_or_b32 v0, v3, s12, v0
	v_and_b32_e32 v4, 4, v4
	v_and_b32_e32 v5, 24, v5
	v_or3_b32 v0, v0, v4, v5
	v_mul_i32_i24_e32 v5, 64, v10
	s_ashr_i32 s27, s0, 6
	v_sub_u32_e32 v2, v2, v5
	s_ashr_i32 s1, s0, 8
	s_lshl_b32 s22, s27, 10
	v_lshlrev_b32_e32 v4, 5, v11
	v_ashrrev_i16_sdwa v2, v224, sext(v2) dst_sel:DWORD dst_unused:UNUSED_PAD src0_sel:DWORD src1_sel:BYTE_0
	v_readlane_b32 s12, v255, 23
	v_and_b32_e32 v4, 32, v4
	v_bfe_i32 v12, v2, 0, 16
	v_readlane_b32 s13, v255, 24
	s_add_u32 s84, s20, s12
	v_add_lshl_u32 v2, v4, v12, 1
	s_addc_u32 s85, s21, s13
	s_add_i32 s23, s22, 0
	v_lshl_add_u32 v0, v0, 11, v2
	s_add_i32 m0, s23, 0x10000
	v_readlane_b32 s12, v255, 27
	global_load_lds_dwordx4 v0, s[84:85]
	s_add_i32 m0, s23, 0x12000
	s_add_u32 s24, s84, 0x40000
	global_load_lds_dwordx4 v130, s[84:85]
	s_addc_u32 s25, s85, 0
	s_add_i32 m0, s23, 0x14000
	v_lshl_add_u32 v134, v3, 11, v2
	global_load_lds_dwordx4 v0, s[24:25]
	s_add_i32 m0, s23, 0x16000
	v_readlane_b32 s13, v255, 28
	global_load_lds_dwordx4 v130, s[24:25]
	s_mov_b32 m0, s23
	s_add_i32 s24, s23, 0x2000
	s_add_i32 s25, s23, 0x4000
	s_nop 0
	global_load_lds_dwordx4 v134, s[12:13]
	s_mov_b32 m0, s24
	s_add_i32 s26, s23, 0x6000
	global_load_lds_dwordx4 v132, s[12:13]
	v_readlane_b32 s12, v255, 29
	s_mov_b32 m0, s25
	v_readlane_b32 s13, v255, 30
	v_mov_b32_e32 v131, v1
	s_cmp_eq_u32 s1, 1
	v_lshl_add_u64 v[2:3], s[84:85], 0, v[0:1]
	s_cselect_b64 s[38:39], -1, 0
	s_cmp_lg_u32 s1, 1
	global_load_lds_dwordx4 v134, s[12:13]
	s_mov_b32 m0, s26
	v_lshl_add_u64 v[4:5], s[84:85], 0, v[130:131]
	global_load_lds_dwordx4 v132, s[12:13]
	s_cbranch_scc1 .LBB0_840
	s_barrier
.LBB0_840:
	s_cmp_eq_u32 s19, 0
	s_cbranch_scc1 .Lmy_rst2_done
	v_cmp_gt_i32_e32 vcc, 0x100, v8
	s_and_saveexec_b64 s[98:99], vcc
	s_cbranch_execz .Lmy_rst2_skip
	s_waitcnt vmcnt(8)
	v_ffbh_u32_e32 v248, v251
	v_min_u32_e32 v248, 32, v248
	v_lshlrev_b64 v[250:251], v248, v[250:251]
	v_min_u32_e32 v250, 1, v250
	v_or_b32_e32 v250, v251, v250
	v_cvt_f32_u32_e32 v250, v250
	v_sub_u32_e32 v251, 32, v248
	v_ldexp_f32 v250, v250, v251
	v_fmamk_f32 v250, v250, 0x30800000, v207
	v_mul_f32_e32 v251, 0x4b800000, v250
	v_cmp_gt_f32_e32 vcc, s16, v250
	s_nop 1
	v_cndmask_b32_e32 v250, v250, v251, vcc
	v_rsq_f32_e32 v250, v250
	s_nop 0
	v_mul_f32_e32 v251, 0x45800000, v250
	v_cndmask_b32_e32 v250, v250, v251, vcc
	ds_write_b32 v249, v250
.Lmy_rst2_skip:
	s_or_b64 exec, exec, s[98:99]
